# v66 plus the MLA epilogue QK^T block rescheduled as well (5 of 6 blocks)
# baseline (speedup 1.0000x reference)
; #define LAS __attribute__((address_space(3)))
; #define MLA_SBAR() __builtin_amdgcn_sched_barrier(0)
; __device__ __forceinline__ void finishSM(f32x16& p0, f32x16& p1, float alpha, float& l_reg, bf16x8& pa0, bf16x8& pa1, bf16x8& pa2, bf16x8& pa3) {
; #pragma unroll
;   for (int r = 0; r < 16; ++r) p1[r] = __builtin_amdgcn_exp2f(p1[r]);
;   float ps = 0;
; #pragma unroll
;   for (int r = 0; r < 16; ++r) ps += p0[r];
; #pragma unroll
;   for (int r = 0; r < 16; ++r) ps += p1[r];
;   { auto rr = __builtin_amdgcn_permlane32_swap(__float_as_uint(ps), __float_as_uint(ps), false, false);
;     ps = __uint_as_float(rr[0]) + __uint_as_float(rr[1]); }
;   l_reg = l_reg * alpha + ps;
;     ...
;   MLA_PK4(p0, 0, pa0); MLA_PK4(p0, 8, pa1); MLA_PK4(p1, 0, pa2); MLA_PK4(p1, 8, pa3);
;     ...
; }
; __device__ __forceinline__ void qkt(f32x16& p0, f32x16& p1, const unsigned Ks, const bf16x8* qr, const unsigned qrl, int r32, int hi) {
;   p0 = f32x16{}; p1 = f32x16{}; __builtin_amdgcn_s_setprio(1);
; #pragma unroll
;   for (int dg = 0; dg < 3; ++dg) {
; #pragma unroll
;     for (int d4 = 0; d4 < 4; ++d4) { const int d0 = dg * 4 + d4;
;       const bf16x8 b0 = *(const LAS bf16x8*)(size_t)(Ks + (unsigned)(r32 * KROW + hi * 16) + (unsigned)(d0 * 32));
;       const bf16x8 b1 = *(const LAS bf16x8*)(size_t)(Ks + (unsigned)(r32 * KROW + hi * 16) + (unsigned)(32 * KROW + d0 * 32));
;       const bf16x8 qv = (dg < 2) ? qr[d0 & 7] : *(const LAS bf16x8*)(size_t)(qrl + (unsigned)(d4 * 32));
;       p0 = __builtin_amdgcn_mfma_f32_32x32x16_bf16(b0, qv, p0, 0, 0, 0);
;       p1 = __builtin_amdgcn_mfma_f32_32x32x16_bf16(b1, qv, p1, 0, 0, 0); }
;     MLA_SBAR(); }
;   __builtin_amdgcn_s_setprio(0);
; }
; __device__ __forceinline__ void attn_body(const GAS bf16* __restrict__ Qb, const int ldq, const GAS bf16* __restrict__ Kn, const GAS bf16* __restrict__ Vh, const int ldkv, const GAS bf16* __restrict__ Kr, ...
;     ...
;   MLA_SBAR(); qkt(pB0, pB1, K_lds + SHM_K, qr, qrl, r32, hi);
;   finishSM(pA0, pA1, alA, l_reg, pa0, pa1, pa2, pa3); MLA_SBAR();
;   pv_d0(o, vb0, pa0, pa1, pa2, pa3); partialSM(pB0, pB1, m_reg, mnB, alB);
.LBB0_2657:
	s_setprio 1
	ds_read_b128 v[64:67], v199 offset:58368
	ds_read_b128 v[168:171], v199 offset:58400
	v_add_u32_e32 v68, 0x11600, v199
	v_add_u32_e32 v161, 0x11640, v199
	s_waitcnt lgkmcnt(1)
	v_mfma_f32_32x32x16_bf16 v[80:95], v[64:67], v[140:143], 0
	ds_read_b128 v[64:67], v68
	s_waitcnt lgkmcnt(1)
	v_mfma_f32_32x32x16_bf16 v[80:95], v[168:171], v[136:139], v[80:95]
	s_waitcnt lgkmcnt(0)
	v_mfma_f32_32x32x16_bf16 v[64:79], v[64:67], v[140:143], 0
	v_add_u32_e32 v140, 0x11620, v199
	ds_read_b128 v[140:143], v140
	s_waitcnt lgkmcnt(0)
	v_mfma_f32_32x32x16_bf16 v[64:79], v[140:143], v[136:139], v[64:79]
	ds_read_b128 v[136:139], v199 offset:58432
	ds_read_b128 v[140:143], v199 offset:58464
	s_waitcnt lgkmcnt(1)
	v_mfma_f32_32x32x16_bf16 v[80:95], v[136:139], v[132:135], v[80:95]
	ds_read_b128 v[136:139], v161
	s_waitcnt lgkmcnt(0)
	v_mfma_f32_32x32x16_bf16 v[64:79], v[136:139], v[132:135], v[64:79]
	v_add_u32_e32 v132, 0x11660, v199
	ds_read_b128 v[132:135], v132
	v_mfma_f32_32x32x16_bf16 v[80:95], v[140:143], v[128:131], v[80:95]
	s_waitcnt lgkmcnt(0)
	v_mfma_f32_32x32x16_bf16 v[64:79], v[132:135], v[128:131], v[64:79]
	ds_read_b128 v[128:131], v199 offset:58496
	ds_read_b128 v[132:135], v199 offset:58528
	v_add_u32_e32 v136, 0x11680, v199
	s_waitcnt lgkmcnt(1)
	v_mfma_f32_32x32x16_bf16 v[80:95], v[128:131], v[124:127], v[80:95]
	ds_read_b128 v[128:131], v136
	s_waitcnt lgkmcnt(1)
	v_mfma_f32_32x32x16_bf16 v[80:95], v[132:135], v[120:123], v[80:95]
	s_waitcnt lgkmcnt(0)
	v_mfma_f32_32x32x16_bf16 v[64:79], v[128:131], v[124:127], v[64:79]
	v_add_u32_e32 v124, 0x116a0, v199
	ds_read_b128 v[124:127], v124
	v_add_u32_e32 v128, 0x116c0, v199
	s_waitcnt lgkmcnt(0)
	v_mfma_f32_32x32x16_bf16 v[64:79], v[124:127], v[120:123], v[64:79]
	ds_read_b128 v[120:123], v199 offset:58560
	ds_read_b128 v[124:127], v199 offset:58592
	s_waitcnt lgkmcnt(1)
	v_mfma_f32_32x32x16_bf16 v[80:95], v[120:123], v[116:119], v[80:95]
	ds_read_b128 v[120:123], v128
	s_waitcnt lgkmcnt(0)
	v_mfma_f32_32x32x16_bf16 v[64:79], v[120:123], v[116:119], v[64:79]
	v_add_u32_e32 v116, 0x116e0, v199
	ds_read_b128 v[116:119], v116
	v_mfma_f32_32x32x16_bf16 v[80:95], v[124:127], v[112:115], v[80:95]
	s_waitcnt lgkmcnt(0)
	v_mfma_f32_32x32x16_bf16 v[64:79], v[116:119], v[112:115], v[64:79]
	ds_read_b128 v[112:115], v199 offset:58624
	ds_read_b128 v[116:119], v193
	ds_read_b128 v[120:123], v199 offset:58656
	v_add_u32_e32 v124, 0x11700, v199
	s_waitcnt lgkmcnt(1)
	v_mfma_f32_32x32x16_bf16 v[80:95], v[112:115], v[116:119], v[80:95]
	ds_read_b128 v[112:115], v124
	v_add_u32_e32 v124, 0x11740, v199
	s_waitcnt lgkmcnt(0)
	v_mfma_f32_32x32x16_bf16 v[64:79], v[112:115], v[116:119], v[64:79]
	v_add_u32_e32 v116, 0x11720, v199
	ds_read_b128 v[116:119], v116
	ds_read_b128 v[112:115], v195
	s_waitcnt lgkmcnt(0)
	v_mfma_f32_32x32x16_bf16 v[80:95], v[120:123], v[112:115], v[80:95]
	v_mfma_f32_32x32x16_bf16 v[64:79], v[116:119], v[112:115], v[64:79]
	ds_read_b128 v[112:115], v199 offset:58688
	ds_read_b128 v[116:119], v196
	ds_read_b128 v[120:123], v199 offset:58720
	s_waitcnt lgkmcnt(1)
	v_mfma_f32_32x32x16_bf16 v[80:95], v[112:115], v[116:119], v[80:95]
	ds_read_b128 v[112:115], v124
	s_waitcnt lgkmcnt(0)
	v_mfma_f32_32x32x16_bf16 v[64:79], v[112:115], v[116:119], v[64:79]
	v_add_u32_e32 v116, 0x11760, v199
	ds_read_b128 v[116:119], v116
	ds_read_b128 v[112:115], v194
	s_waitcnt lgkmcnt(0)
	v_mfma_f32_32x32x16_bf16 v[80:95], v[120:123], v[112:115], v[80:95]
	v_mfma_f32_32x32x16_bf16 v[64:79], v[116:119], v[112:115], v[64:79]
	s_setprio 0
	v_exp_f32_e32 v112, v96
	v_add_f32_e32 v96, 0, v158
	v_add_f32_e32 v96, v159, v96
	v_add_f32_e32 v96, v156, v96
	v_add_f32_e32 v96, v157, v96
	v_add_f32_e32 v96, v154, v96
	v_add_f32_e32 v96, v155, v96
	v_add_f32_e32 v96, v152, v96
	v_add_f32_e32 v96, v153, v96
	v_add_f32_e32 v96, v150, v96
	v_add_f32_e32 v96, v151, v96
	v_add_f32_e32 v96, v148, v96
	v_add_f32_e32 v96, v149, v96
	v_add_f32_e32 v96, v146, v96
	v_exp_f32_e32 v113, v97
	v_add_f32_e32 v96, v147, v96
	v_exp_f32_e32 v114, v98
	v_add_f32_e32 v96, v144, v96
	v_exp_f32_e32 v115, v99
	v_add_f32_e32 v96, v145, v96
	v_exp_f32_e32 v116, v100
	v_add_f32_e32 v96, v112, v96
	v_exp_f32_e32 v117, v101
	v_add_f32_e32 v96, v113, v96
	v_exp_f32_e32 v118, v102
	v_add_f32_e32 v96, v114, v96
	v_exp_f32_e32 v119, v103
	v_add_f32_e32 v96, v115, v96
	v_exp_f32_e32 v120, v104
	v_add_f32_e32 v96, v116, v96
	v_exp_f32_e32 v121, v105
	v_add_f32_e32 v96, v117, v96
	v_exp_f32_e32 v122, v106
	v_add_f32_e32 v96, v118, v96
	v_exp_f32_e32 v123, v107
	v_add_f32_e32 v96, v119, v96
	v_exp_f32_e32 v124, v108
	v_add_f32_e32 v96, v120, v96
	v_exp_f32_e32 v125, v109
	v_add_f32_e32 v96, v121, v96
	v_exp_f32_e32 v126, v110
	v_add_f32_e32 v96, v122, v96
	v_exp_f32_e32 v127, v111
	v_add_f32_e32 v96, v123, v96
	v_add_f32_e32 v96, v124, v96
	v_add_f32_e32 v96, v125, v96
	v_add_f32_e32 v96, v126, v96
	v_add_f32_e32 v96, v127, v96
	v_mov_b32_e32 v97, v96
	v_cvt_pk_bf16_f32 v98, v158, v159
	v_cvt_pk_bf16_f32 v99, v156, v157
	v_cvt_pk_bf16_f32 v100, v154, v155
	v_cvt_pk_bf16_f32 v101, v152, v153
	s_nop 1
	v_permlane32_swap_b32_e32 v96, v97
	v_permlane32_swap_b32_e32 v98, v100
	v_permlane32_swap_b32_e32 v99, v101
	v_cvt_pk_bf16_f32 v102, v150, v151
	v_cvt_pk_bf16_f32 v103, v148, v149
	v_cvt_pk_bf16_f32 v104, v146, v147
	v_cvt_pk_bf16_f32 v105, v144, v145
	v_cvt_pk_bf16_f32 v106, v112, v113
	v_cvt_pk_bf16_f32 v107, v114, v115
	v_cvt_pk_bf16_f32 v108, v116, v117
	v_cvt_pk_bf16_f32 v109, v118, v119
	v_cvt_pk_bf16_f32 v110, v120, v121
	v_cvt_pk_bf16_f32 v111, v122, v123
	v_cvt_pk_bf16_f32 v112, v124, v125
	v_cvt_pk_bf16_f32 v113, v126, v127
	s_nop 0
	v_permlane32_swap_b32_e32 v102, v104
	v_permlane32_swap_b32_e32 v103, v105
	v_permlane32_swap_b32_e32 v106, v108
	v_permlane32_swap_b32_e32 v107, v109
	v_permlane32_swap_b32_e32 v110, v112
	v_permlane32_swap_b32_e32 v111, v113
	s_setprio 1
	ds_read_b64_tr_b16 v[114:115], v192 offset:0
	ds_read_b64_tr_b16 v[116:117], v192 offset:0x800
	ds_read_b64_tr_b16 v[118:119], v192 offset:0x1000
	ds_read_b64_tr_b16 v[120:121], v192 offset:0x1800
	ds_read_b64_tr_b16 v[122:123], v192 offset:0x2000
	ds_read_b64_tr_b16 v[124:125], v192 offset:0x2800
	ds_read_b64_tr_b16 v[126:127], v192 offset:0x3000
	ds_read_b64_tr_b16 v[128:129], v192 offset:0x3800
	s_waitcnt lgkmcnt(0)
; #define MLA_SBAR() __builtin_amdgcn_sched_barrier(0)
; #define MLA_RESC(a) do { if (__any((a) < 1.f)) { if (hi == 0) al_l[r32] = (a); asm volatile("s_waitcnt lgkmcnt(0)" ::: "memory"); \
;     _Pragma("unroll") for (int d = 0; d < 4; ++d) _Pragma("unroll") for (int r = 0; r < 16; ++r) o[d][r] *= al_l[crow(r, hi)]; } } while (0)
; template <int D0> __device__ __forceinline__ void pv_one(f32x16& od, int vb, bf16x8 pa0, bf16x8 pa1, bf16x8 pa2, bf16x8 pa3) {
;   const s16x4 l0 = tr_read<v_rd_off(D0, 0, 0)>(vb), h0 = tr_read<v_rd_off(D0, 0, 1)>(vb), l1 = tr_read<v_rd_off(D0, 1, 0)>(vb), h1 = tr_read<v_rd_off(D0, 1, 1)>(vb);
;   const s16x4 l2 = tr_read<v_rd_off(D0, 2, 0)>(vb), h2 = tr_read<v_rd_off(D0, 2, 1)>(vb), l3 = tr_read<v_rd_off(D0, 3, 0)>(vb), h3 = tr_read<v_rd_off(D0, 3, 1)>(vb);
;   asm volatile("s_waitcnt lgkmcnt(0)" ::: "memory"); MLA_SBAR();
;     ...
;   od = __builtin_amdgcn_mfma_f32_32x32x16_bf16(pa0, MLA_PK(l0, h0), od, 0, 0, 0);
;   od = __builtin_amdgcn_mfma_f32_32x32x16_bf16(pa1, MLA_PK(l1, h1), od, 0, 0, 0);
;   od = __builtin_amdgcn_mfma_f32_32x32x16_bf16(pa2, MLA_PK(l2, h2), od, 0, 0, 0);
;   od = __builtin_amdgcn_mfma_f32_32x32x16_bf16(pa3, MLA_PK(l3, h3), od, 0, 0, 0);
;     ...
; }
; __device__ __forceinline__ void pv_d0(f32x16* o, int vb, bf16x8 pa0, bf16x8 pa1, bf16x8 pa2, bf16x8 pa3) {
;   __builtin_amdgcn_s_setprio(1);
;   pv_one<0>(o[0], vb, pa0, pa1, pa2, pa3); pv_one<1>(o[1], vb, pa0, pa1, pa2, pa3); pv_one<2>(o[2], vb, pa0, pa1, pa2, pa3); pv_one<3>(o[3], vb, pa0, pa1, pa2, pa3);
;   __builtin_amdgcn_s_setprio(0);
; }
; __device__ __forceinline__ void attn_body(const GAS bf16* __restrict__ Qb, const int ldq, const GAS bf16* __restrict__ Kn, const GAS bf16* __restrict__ Vh, const int ldkv, const GAS bf16* __restrict__ Kr, ...
;     ...
;   pv_d0(o, vb0, pa0, pa1, pa2, pa3); partialSM(pB0, pB1, m_reg, mnB, alB);
;   __syncthreads(); MLA_RESC(alB);
	s_nop 0
	v_mfma_f32_32x32x16_bf16 v[0:15], v[98:101], v[114:117], v[0:15]
	ds_read_b64_tr_b16 v[114:115], v192 offset:0x200
	ds_read_b64_tr_b16 v[116:117], v192 offset:0xa00
	v_mfma_f32_32x32x16_bf16 v[0:15], v[102:105], v[118:121], v[0:15]
	ds_read_b64_tr_b16 v[118:119], v192 offset:0x1200
	ds_read_b64_tr_b16 v[120:121], v192 offset:0x1a00
	v_mfma_f32_32x32x16_bf16 v[0:15], v[106:109], v[122:125], v[0:15]
	ds_read_b64_tr_b16 v[122:123], v192 offset:0x2200
	ds_read_b64_tr_b16 v[124:125], v192 offset:0x2a00
	ds_read_b64_tr_b16 v[130:131], v192 offset:0x3200
	ds_read_b64_tr_b16 v[132:133], v192 offset:0x3a00
	s_waitcnt lgkmcnt(0)
	v_mfma_f32_32x32x16_bf16 v[0:15], v[110:113], v[126:129], v[0:15]
	v_mfma_f32_32x32x16_bf16 v[48:63], v[98:101], v[114:117], v[48:63]
	ds_read_b64_tr_b16 v[114:115], v192 offset:0x400
	ds_read_b64_tr_b16 v[116:117], v192 offset:0xc00
	v_mfma_f32_32x32x16_bf16 v[48:63], v[102:105], v[118:121], v[48:63]
	ds_read_b64_tr_b16 v[118:119], v192 offset:0x1400
	ds_read_b64_tr_b16 v[120:121], v192 offset:0x1c00
	v_mfma_f32_32x32x16_bf16 v[48:63], v[106:109], v[122:125], v[48:63]
	ds_read_b64_tr_b16 v[122:123], v192 offset:0x2400
	ds_read_b64_tr_b16 v[124:125], v192 offset:0x2c00
	ds_read_b64_tr_b16 v[126:127], v192 offset:0x3400
	ds_read_b64_tr_b16 v[128:129], v192 offset:0x3c00
	s_waitcnt lgkmcnt(0)
	v_mfma_f32_32x32x16_bf16 v[48:63], v[110:113], v[130:133], v[48:63]
	v_mfma_f32_32x32x16_bf16 v[32:47], v[98:101], v[114:117], v[32:47]
	ds_read_b64_tr_b16 v[114:115], v192 offset:0x600
	ds_read_b64_tr_b16 v[116:117], v192 offset:0xe00
	v_mfma_f32_32x32x16_bf16 v[32:47], v[102:105], v[118:121], v[32:47]
	ds_read_b64_tr_b16 v[118:119], v192 offset:0x1600
	ds_read_b64_tr_b16 v[120:121], v192 offset:0x1e00
	v_mfma_f32_32x32x16_bf16 v[32:47], v[106:109], v[122:125], v[32:47]
	ds_read_b64_tr_b16 v[122:123], v192 offset:0x2600
	ds_read_b64_tr_b16 v[124:125], v192 offset:0x2e00
	ds_read_b64_tr_b16 v[130:131], v192 offset:0x3600
	ds_read_b64_tr_b16 v[132:133], v192 offset:0x3e00
	s_waitcnt lgkmcnt(0)
	v_mfma_f32_32x32x16_bf16 v[32:47], v[110:113], v[126:129], v[32:47]
	v_mfma_f32_32x32x16_bf16 v[16:31], v[98:101], v[114:117], v[16:31]
	v_mfma_f32_32x32x16_bf16 v[16:31], v[102:105], v[118:121], v[16:31]
	v_mfma_f32_32x32x16_bf16 v[16:31], v[106:109], v[122:125], v[16:31]
	v_mfma_f32_32x32x16_bf16 v[16:31], v[110:113], v[130:133], v[16:31]
	s_setprio 0
	v_max_f32_e32 v98, v81, v81
	v_max_f32_e32 v99, v80, v80
	v_max_f32_e32 v98, v99, v98
	v_max3_f32 v98, v98, v82, v83
	v_max3_f32 v98, v98, v84, v85
	v_max3_f32 v98, v98, v86, v87
	v_max3_f32 v98, v98, v88, v89
	v_max3_f32 v98, v98, v90, v91
	v_max3_f32 v98, v98, v92, v93
	v_max3_f32 v98, v98, v94, v95
	v_max3_f32 v98, v98, v64, v65
	v_max3_f32 v98, v98, v66, v67
	v_max3_f32 v98, v98, v68, v69
	v_max3_f32 v98, v98, v70, v71
	v_max3_f32 v98, v98, v72, v73
	v_max3_f32 v98, v98, v74, v75
	v_max3_f32 v98, v98, v76, v77
	v_max3_f32 v98, v98, v78, v79
	v_mov_b32_e32 v99, v98
	s_nop 1
	v_permlane32_swap_b32_e32 v98, v99
	v_max_f32_e32 v99, v99, v99
	v_max_f32_e32 v98, v98, v98
	v_max_f32_e32 v98, v98, v99
	v_sub_f32_e32 v99, v98, v160
	v_cmp_ge_f32_e32 vcc, s75, v99
	v_max_f32_e32 v99, v160, v160
	v_max_f32_e32 v99, v99, v98
	v_sub_f32_e32 v98, v160, v99
	v_mul_f32_e32 v98, 0x3dd53b94, v98
	v_exp_f32_e32 v98, v98
	s_cmp_eq_u64 vcc, exec
	s_cselect_b64 s[4:5], -1, 0
	v_cndmask_b32_e64 v98, v98, 1.0, s[4:5]
	v_cmp_gt_f32_e32 vcc, 1.0, v98
	s_barrier
	s_cbranch_vccz .LBB0_2661
	s_and_saveexec_b64 s[60:61], s[2:3]
	ds_write_b32 v177, v98 offset:128
	s_or_b64 exec, exec, s[60:61]
	s_waitcnt lgkmcnt(0)
	v_add_u32_e32 v114, v167, v164
	ds_read2_b32 v[100:101], v114 offset0:48 offset1:49
	ds_read2_b32 v[102:103], v114 offset0:50 offset1:51
	ds_read2_b32 v[104:105], v114 offset0:56 offset1:57
	ds_read2_b32 v[106:107], v114 offset0:58 offset1:59
	ds_read2_b32 v[108:109], v114 offset0:32 offset1:33
	ds_read2_b32 v[110:111], v114 offset0:34 offset1:35
	ds_read2_b32 v[112:113], v114 offset0:40 offset1:41
	ds_read2_b32 v[114:115], v114 offset0:42 offset1:43
	s_waitcnt lgkmcnt(4)
	v_pk_mul_f32 v[14:15], v[14:15], v[106:107]
	v_pk_mul_f32 v[12:13], v[12:13], v[104:105]
	v_pk_mul_f32 v[10:11], v[10:11], v[102:103]
	v_pk_mul_f32 v[8:9], v[8:9], v[100:101]
	s_waitcnt lgkmcnt(0)
	v_pk_mul_f32 v[6:7], v[6:7], v[114:115]
	v_pk_mul_f32 v[4:5], v[4:5], v[112:113]
	v_pk_mul_f32 v[2:3], v[2:3], v[110:111]
	v_pk_mul_f32 v[0:1], v[0:1], v[108:109]
	v_pk_mul_f32 v[62:63], v[62:63], v[106:107]
	v_pk_mul_f32 v[60:61], v[60:61], v[104:105]
	v_pk_mul_f32 v[58:59], v[58:59], v[102:103]
	v_pk_mul_f32 v[56:57], v[56:57], v[100:101]
	v_pk_mul_f32 v[54:55], v[54:55], v[114:115]
	v_pk_mul_f32 v[52:53], v[52:53], v[112:113]
	v_pk_mul_f32 v[50:51], v[50:51], v[110:111]
	v_pk_mul_f32 v[48:49], v[48:49], v[108:109]
	v_pk_mul_f32 v[46:47], v[46:47], v[106:107]
	v_pk_mul_f32 v[44:45], v[44:45], v[104:105]
	v_pk_mul_f32 v[42:43], v[42:43], v[102:103]
	v_pk_mul_f32 v[40:41], v[40:41], v[100:101]
	v_pk_mul_f32 v[38:39], v[38:39], v[114:115]
	v_pk_mul_f32 v[36:37], v[36:37], v[112:113]
	v_pk_mul_f32 v[34:35], v[34:35], v[110:111]
	v_pk_mul_f32 v[32:33], v[32:33], v[108:109]
	v_pk_mul_f32 v[30:31], v[30:31], v[106:107]
	v_pk_mul_f32 v[28:29], v[28:29], v[104:105]
	v_pk_mul_f32 v[26:27], v[26:27], v[102:103]
	v_pk_mul_f32 v[24:25], v[24:25], v[100:101]
	v_pk_mul_f32 v[22:23], v[22:23], v[114:115]
	v_pk_mul_f32 v[20:21], v[20:21], v[112:113]
	v_pk_mul_f32 v[18:19], v[18:19], v[110:111]
	v_pk_mul_f32 v[16:17], v[16:17], v[108:109]
